# grid barrier all-to-all release: every XCD leader adds to all XGEN words, everyone polls own XGEN >= (round+1)*nx; TOP/TOPGEN hop and second division removed
# baseline (speedup 1.0000x reference)
; __device__ __forceinline__ unsigned xb_ld(unsigned* p)              { return __hip_atomic_load(p, __ATOMIC_RELAXED, __HIP_MEMORY_SCOPE_AGENT); }
; __device__ __forceinline__ unsigned xb_add(unsigned* p, unsigned v) { return __hip_atomic_fetch_add(p, v, __ATOMIC_RELAXED, __HIP_MEMORY_SCOPE_AGENT); }
; #define XB_SPIN(cond, bar) do { unsigned _sp = 0; while (cond) { __builtin_amdgcn_s_sleep(1); \
;     if ((++_sp & 255u) == 0u) { if (xb_ld(&(bar)[XB_TMO])) break; if (_sp > XB_SPIN_CAP) { atomicAdd(&(bar)[XB_TMO], 1u); break; } } } } while (0)
; __device__ __forceinline__ void xcd_barrier(const XcdBarrier& b) {
;     ...
;         const unsigned old = xb_add(&bar[XB_XSUB(b.x)], 1u);
;         const unsigned gen = old / nloc;
;         if (old + 1u == (gen + 1u) * nloc) {
;     ...
;             XB_SPIN(xb_ld(&bar[XB_XGEN(b.x)]) == gen, bar);
.LBB0_43:
	s_or_b64 exec, exec, s[8:9]
	v_cvt_f32_u32_e32 v5, v3
	s_waitcnt vmcnt(0)
	v_readfirstlane_b32 s6, v4
	v_sub_u32_e32 v4, 0, v3
	v_rcp_iflag_f32_e32 v5, v5
	v_add_u32_e32 v6, s6, v2
	v_mul_f32_e32 v5, 0x4f7ffffe, v5
	v_cvt_u32_f32_e32 v5, v5
	v_mul_lo_u32 v2, v4, v5
	v_mul_hi_u32 v2, v5, v2
	v_add_u32_e32 v2, v5, v2
	v_mul_hi_u32 v2, v6, v2
	v_mul_lo_u32 v4, v2, v3
	v_sub_u32_e32 v4, v6, v4
	v_add_u32_e32 v5, 1, v2
	v_cmp_ge_u32_e32 vcc, v4, v3
	s_nop 1
	v_cndmask_b32_e32 v2, v2, v5, vcc
	v_sub_u32_e32 v5, v4, v3
	v_cndmask_b32_e32 v4, v4, v5, vcc
	v_add_u32_e32 v5, 1, v2
	v_cmp_ge_u32_e32 vcc, v4, v3
	v_add_u32_e32 v4, 1, v6
	s_nop 0
	v_cndmask_b32_e32 v2, v2, v5, vcc
	v_mul_lo_u32 v5, v3, v2
	v_add_u32_e32 v3, v5, v3
	v_cmp_ne_u32_e32 vcc, v4, v3
	s_and_saveexec_b64 s[6:7], vcc
	s_xor_b64 s[6:7], exec, s[6:7]
	s_cbranch_execz .LBB0_57
	s_waitcnt lgkmcnt(0)
	v_add_u32_e32 v2, 1, v2
	v_mul_lo_u32 v2, v2, v1
	v_mov_b32_e32 v1, 0x2000
	global_load_dword v1, v1, s[4:5] offset:1024 sc1
	s_add_u32 s12, s4, 0x2400
	s_addc_u32 s13, s5, 0
	s_waitcnt vmcnt(0)
	v_cmp_lt_u32_e32 vcc, v1, v2
	s_and_saveexec_b64 s[8:9], vcc
	s_cbranch_execz .LBB0_56
	s_add_u32 s10, s2, 0x1200
	s_addc_u32 s11, s3, 0
	s_mov_b32 s24, 1
	s_mov_b64 s[14:15], 0
	v_mov_b32_e32 v1, 0
	s_branch .LBB0_47

; __device__ __forceinline__ unsigned xb_ld(unsigned* p)              { return __hip_atomic_load(p, __ATOMIC_RELAXED, __HIP_MEMORY_SCOPE_AGENT); }
; #define XB_SPIN(cond, bar) do { unsigned _sp = 0; while (cond) { __builtin_amdgcn_s_sleep(1); \
;     if ((++_sp & 255u) == 0u) { if (xb_ld(&(bar)[XB_TMO])) break; if (_sp > XB_SPIN_CAP) { atomicAdd(&(bar)[XB_TMO], 1u); break; } } } } while (0)
; __device__ __forceinline__ void xcd_barrier(const XcdBarrier& b) {
;     ...
;             XB_SPIN(xb_ld(&bar[XB_XGEN(b.x)]) == gen, bar);
.LBB0_49:
	global_load_dword v3, v1, s[12:13] sc1
	s_add_i32 s24, s24, 1
	s_mov_b64 s[20:21], -1
	s_waitcnt vmcnt(0)
	v_cmp_ge_u32_e32 vcc, v3, v2
	s_orn2_b64 s[18:19], vcc, exec
	s_branch .LBB0_46

; __device__ __forceinline__ unsigned xb_ld(unsigned* p)              { return __hip_atomic_load(p, __ATOMIC_RELAXED, __HIP_MEMORY_SCOPE_AGENT); }
; __device__ __forceinline__ unsigned xb_add(unsigned* p, unsigned v) { return __hip_atomic_fetch_add(p, v, __ATOMIC_RELAXED, __HIP_MEMORY_SCOPE_AGENT); }
; #define XB_SPIN(cond, bar) do { unsigned _sp = 0; while (cond) { __builtin_amdgcn_s_sleep(1); \
;     if ((++_sp & 255u) == 0u) { if (xb_ld(&(bar)[XB_TMO])) break; if (_sp > XB_SPIN_CAP) { atomicAdd(&(bar)[XB_TMO], 1u); break; } } } } while (0)
; __device__ __forceinline__ void xcd_barrier(const XcdBarrier& b) {
;     ...
;         if (old + 1u == (gen + 1u) * nloc) {
;             __builtin_amdgcn_fence(__ATOMIC_RELEASE, "agent");
;             asm volatile("s_waitcnt vmcnt(0)" ::: "memory");
;             const unsigned og = xb_add(&bar[XB_TOP], 1u);
;             const unsigned tg = og / nx;
;             if (og + 1u == (tg + 1u) * nx) xb_add(&bar[XB_TOPGEN], 1u);
;             else XB_SPIN(xb_ld(&bar[XB_TOPGEN]) == tg, bar);
;             __builtin_amdgcn_fence(__ATOMIC_ACQUIRE, "agent");
;             xb_add(&bar[XB_XGEN(b.x)], 1u);
;             asm volatile("s_waitcnt vmcnt(0)" ::: "memory");
;         } else {
;             XB_SPIN(xb_ld(&bar[XB_XGEN(b.x)]) == gen, bar);
;             __builtin_amdgcn_fence(__ATOMIC_ACQUIRE, "agent");
;             asm volatile("s_waitcnt vmcnt(0)" ::: "memory");
.LBB0_57:
	s_andn2_saveexec_b64 s[6:7], s[6:7]
	s_cbranch_execz .LBB0_77
	s_mov_b64 s[6:7], exec
	buffer_wbl2 sc1
	s_waitcnt lgkmcnt(0)
	s_waitcnt vmcnt(0)
	v_add_u32_e32 v2, 1, v2
	v_mul_lo_u32 v2, v2, v1
	v_mov_b32_e32 v5, 0x3400
	v_mov_b32_e32 v6, 1
	global_atomic_add v5, v6, s[2:3]
	global_atomic_add v5, v6, s[2:3] offset:256
	global_atomic_add v5, v6, s[2:3] offset:512
	global_atomic_add v5, v6, s[2:3] offset:768
	global_atomic_add v5, v6, s[2:3] offset:1024
	global_atomic_add v5, v6, s[2:3] offset:1280
	global_atomic_add v5, v6, s[2:3] offset:1536
	global_atomic_add v5, v6, s[2:3] offset:1792
	global_atomic_add v5, v6, s[2:3] offset:2048
	global_atomic_add v5, v6, s[2:3] offset:2304
	global_atomic_add v5, v6, s[2:3] offset:2560
	global_atomic_add v5, v6, s[2:3] offset:2816
	global_atomic_add v5, v6, s[2:3] offset:3072
	global_atomic_add v5, v6, s[2:3] offset:3328
	global_atomic_add v5, v6, s[2:3] offset:3584
	global_atomic_add v5, v6, s[2:3] offset:3840
	s_add_u32 s8, s4, 0x2400
	s_addc_u32 s9, s5, 0
	v_mov_b32_e32 v4, 0
	s_mov_b32 s10, 0
.Lxb_spin_9:
	global_load_dword v1, v4, s[8:9] sc1
	s_add_i32 s10, s10, 1
	s_waitcnt vmcnt(0)
	v_cmp_ge_u32_e32 vcc, v1, v2
	s_cbranch_vccnz .Lxb_done_9
	s_sleep 1
	s_cmp_lt_u32 s10, 0x8000
	s_cbranch_scc1 .Lxb_spin_9
	s_add_u32 s8, s2, 0x1200
	s_addc_u32 s9, s3, 0
	global_atomic_add v4, v6, s[8:9]
.Lxb_done_9:
	s_waitcnt vmcnt(0)
	buffer_inv sc1
	s_waitcnt vmcnt(0)

; __device__ __forceinline__ unsigned xb_ld(unsigned* p)              { return __hip_atomic_load(p, __ATOMIC_RELAXED, __HIP_MEMORY_SCOPE_AGENT); }
; __device__ __forceinline__ unsigned xb_add(unsigned* p, unsigned v) { return __hip_atomic_fetch_add(p, v, __ATOMIC_RELAXED, __HIP_MEMORY_SCOPE_AGENT); }
; #define XB_SPIN(cond, bar) do { unsigned _sp = 0; while (cond) { __builtin_amdgcn_s_sleep(1); \
;     if ((++_sp & 255u) == 0u) { if (xb_ld(&(bar)[XB_TMO])) break; if (_sp > XB_SPIN_CAP) { atomicAdd(&(bar)[XB_TMO], 1u); break; } } } } while (0)
; __device__ __forceinline__ void xcd_barrier(const XcdBarrier& b) {
;     ...
;         const unsigned old = xb_add(&bar[XB_XSUB(b.x)], 1u);
;         const unsigned gen = old / nloc;
;         if (old + 1u == (gen + 1u) * nloc) {
;     ...
;             XB_SPIN(xb_ld(&bar[XB_XGEN(b.x)]) == gen, bar);
.LBB0_137:
	s_or_b64 exec, exec, s[8:9]
	v_cvt_f32_u32_e32 v6, v4
	s_waitcnt vmcnt(0)
	v_readfirstlane_b32 s6, v5
	v_sub_u32_e32 v5, 0, v4
	v_rcp_iflag_f32_e32 v6, v6
	v_add_u32_e32 v7, s6, v3
	v_mul_f32_e32 v6, 0x4f7ffffe, v6
	v_cvt_u32_f32_e32 v6, v6
	v_mul_lo_u32 v3, v5, v6
	v_mul_hi_u32 v3, v6, v3
	v_add_u32_e32 v3, v6, v3
	v_mul_hi_u32 v3, v7, v3
	v_mul_lo_u32 v5, v3, v4
	v_sub_u32_e32 v5, v7, v5
	v_add_u32_e32 v6, 1, v3
	v_cmp_ge_u32_e32 vcc, v5, v4
	s_nop 1
	v_cndmask_b32_e32 v3, v3, v6, vcc
	v_sub_u32_e32 v6, v5, v4
	v_cndmask_b32_e32 v5, v5, v6, vcc
	v_add_u32_e32 v6, 1, v3
	v_cmp_ge_u32_e32 vcc, v5, v4
	v_add_u32_e32 v5, 1, v7
	s_nop 0
	v_cndmask_b32_e32 v3, v3, v6, vcc
	v_mul_lo_u32 v6, v4, v3
	v_add_u32_e32 v4, v6, v4
	v_cmp_ne_u32_e32 vcc, v5, v4
	s_and_saveexec_b64 s[6:7], vcc
	s_xor_b64 s[6:7], exec, s[6:7]
	s_cbranch_execz .LBB0_151
	s_waitcnt lgkmcnt(0)
	v_add_u32_e32 v3, 1, v3
	v_mul_lo_u32 v3, v3, v2
	v_mov_b32_e32 v2, 0x2000
	global_load_dword v2, v2, s[4:5] offset:1024 sc1
	s_add_u32 s12, s4, 0x2400
	s_addc_u32 s13, s5, 0
	s_waitcnt vmcnt(0)
	v_cmp_lt_u32_e32 vcc, v2, v3
	s_and_saveexec_b64 s[8:9], vcc
	s_cbranch_execz .LBB0_150
	s_add_u32 s10, s2, 0x1200
	s_addc_u32 s11, s3, 0
	s_mov_b32 s26, 1
	s_mov_b64 s[16:17], 0
	s_branch .LBB0_141

; __device__ __forceinline__ unsigned xb_ld(unsigned* p)              { return __hip_atomic_load(p, __ATOMIC_RELAXED, __HIP_MEMORY_SCOPE_AGENT); }
; #define XB_SPIN(cond, bar) do { unsigned _sp = 0; while (cond) { __builtin_amdgcn_s_sleep(1); \
;     if ((++_sp & 255u) == 0u) { if (xb_ld(&(bar)[XB_TMO])) break; if (_sp > XB_SPIN_CAP) { atomicAdd(&(bar)[XB_TMO], 1u); break; } } } } while (0)
; __device__ __forceinline__ void xcd_barrier(const XcdBarrier& b) {
;     ...
;             XB_SPIN(xb_ld(&bar[XB_XGEN(b.x)]) == gen, bar);
.LBB0_143:
	global_load_dword v2, v35, s[12:13] sc1
	s_add_i32 s26, s26, 1
	s_mov_b64 s[22:23], -1
	s_waitcnt vmcnt(0)
	v_cmp_ge_u32_e32 vcc, v2, v3
	s_orn2_b64 s[20:21], vcc, exec
	s_branch .LBB0_140

; __device__ __forceinline__ unsigned xb_ld(unsigned* p)              { return __hip_atomic_load(p, __ATOMIC_RELAXED, __HIP_MEMORY_SCOPE_AGENT); }
; __device__ __forceinline__ unsigned xb_add(unsigned* p, unsigned v) { return __hip_atomic_fetch_add(p, v, __ATOMIC_RELAXED, __HIP_MEMORY_SCOPE_AGENT); }
; #define XB_SPIN(cond, bar) do { unsigned _sp = 0; while (cond) { __builtin_amdgcn_s_sleep(1); \
;     if ((++_sp & 255u) == 0u) { if (xb_ld(&(bar)[XB_TMO])) break; if (_sp > XB_SPIN_CAP) { atomicAdd(&(bar)[XB_TMO], 1u); break; } } } } while (0)
; __device__ __forceinline__ void xcd_barrier(const XcdBarrier& b) {
;     ...
;         if (old + 1u == (gen + 1u) * nloc) {
;             __builtin_amdgcn_fence(__ATOMIC_RELEASE, "agent");
;             asm volatile("s_waitcnt vmcnt(0)" ::: "memory");
;             const unsigned og = xb_add(&bar[XB_TOP], 1u);
;             const unsigned tg = og / nx;
;             if (og + 1u == (tg + 1u) * nx) xb_add(&bar[XB_TOPGEN], 1u);
;             else XB_SPIN(xb_ld(&bar[XB_TOPGEN]) == tg, bar);
;             __builtin_amdgcn_fence(__ATOMIC_ACQUIRE, "agent");
;             xb_add(&bar[XB_XGEN(b.x)], 1u);
;             asm volatile("s_waitcnt vmcnt(0)" ::: "memory");
;         } else {
;             XB_SPIN(xb_ld(&bar[XB_XGEN(b.x)]) == gen, bar);
;             __builtin_amdgcn_fence(__ATOMIC_ACQUIRE, "agent");
;             asm volatile("s_waitcnt vmcnt(0)" ::: "memory");
.LBB0_151:
	s_andn2_saveexec_b64 s[6:7], s[6:7]
	s_cbranch_execz .LBB0_171
	s_mov_b64 s[8:9], exec
	buffer_wbl2 sc1
	s_waitcnt lgkmcnt(0)
	s_waitcnt vmcnt(0)
	v_add_u32_e32 v3, 1, v3
	v_mul_lo_u32 v3, v3, v2
	v_mov_b32_e32 v5, 0x3400
	v_mov_b32_e32 v6, 1
	global_atomic_add v5, v6, s[2:3]
	global_atomic_add v5, v6, s[2:3] offset:256
	global_atomic_add v5, v6, s[2:3] offset:512
	global_atomic_add v5, v6, s[2:3] offset:768
	global_atomic_add v5, v6, s[2:3] offset:1024
	global_atomic_add v5, v6, s[2:3] offset:1280
	global_atomic_add v5, v6, s[2:3] offset:1536
	global_atomic_add v5, v6, s[2:3] offset:1792
	global_atomic_add v5, v6, s[2:3] offset:2048
	global_atomic_add v5, v6, s[2:3] offset:2304
	global_atomic_add v5, v6, s[2:3] offset:2560
	global_atomic_add v5, v6, s[2:3] offset:2816
	global_atomic_add v5, v6, s[2:3] offset:3072
	global_atomic_add v5, v6, s[2:3] offset:3328
	global_atomic_add v5, v6, s[2:3] offset:3584
	global_atomic_add v5, v6, s[2:3] offset:3840
	s_add_u32 s8, s4, 0x2400
	s_addc_u32 s9, s5, 0
	v_mov_b32_e32 v4, 0
	s_mov_b32 s10, 0
.Lxb_spin_8:
	global_load_dword v2, v4, s[8:9] sc1
	s_add_i32 s10, s10, 1
	s_waitcnt vmcnt(0)
	v_cmp_ge_u32_e32 vcc, v2, v3
	s_cbranch_vccnz .Lxb_done_8
	s_sleep 1
	s_cmp_lt_u32 s10, 0x8000
	s_cbranch_scc1 .Lxb_spin_8
	s_add_u32 s8, s2, 0x1200
	s_addc_u32 s9, s3, 0
	global_atomic_add v4, v6, s[8:9]

; __device__ __forceinline__ unsigned xb_ld(unsigned* p)              { return __hip_atomic_load(p, __ATOMIC_RELAXED, __HIP_MEMORY_SCOPE_AGENT); }
; __device__ __forceinline__ unsigned xb_add(unsigned* p, unsigned v) { return __hip_atomic_fetch_add(p, v, __ATOMIC_RELAXED, __HIP_MEMORY_SCOPE_AGENT); }
; #define XB_SPIN(cond, bar) do { unsigned _sp = 0; while (cond) { __builtin_amdgcn_s_sleep(1); \
;     if ((++_sp & 255u) == 0u) { if (xb_ld(&(bar)[XB_TMO])) break; if (_sp > XB_SPIN_CAP) { atomicAdd(&(bar)[XB_TMO], 1u); break; } } } } while (0)
; __device__ __forceinline__ void xcd_barrier(const XcdBarrier& b) {
;     ...
;         const unsigned old = xb_add(&bar[XB_XSUB(b.x)], 1u);
;         const unsigned gen = old / nloc;
;         if (old + 1u == (gen + 1u) * nloc) {
;     ...
;             XB_SPIN(xb_ld(&bar[XB_XGEN(b.x)]) == gen, bar);
.LBB0_318:
	s_or_b64 exec, exec, s[8:9]
	v_cvt_f32_u32_e32 v6, v4
	s_waitcnt vmcnt(0)
	v_readfirstlane_b32 s6, v5
	v_sub_u32_e32 v5, 0, v4
	v_rcp_iflag_f32_e32 v6, v6
	v_add_u32_e32 v7, s6, v3
	v_mul_f32_e32 v6, 0x4f7ffffe, v6
	v_cvt_u32_f32_e32 v6, v6
	v_mul_lo_u32 v3, v5, v6
	v_mul_hi_u32 v3, v6, v3
	v_add_u32_e32 v3, v6, v3
	v_mul_hi_u32 v3, v7, v3
	v_mul_lo_u32 v5, v3, v4
	v_sub_u32_e32 v5, v7, v5
	v_add_u32_e32 v6, 1, v3
	v_cmp_ge_u32_e32 vcc, v5, v4
	s_nop 1
	v_cndmask_b32_e32 v3, v3, v6, vcc
	v_sub_u32_e32 v6, v5, v4
	v_cndmask_b32_e32 v5, v5, v6, vcc
	v_add_u32_e32 v6, 1, v3
	v_cmp_ge_u32_e32 vcc, v5, v4
	v_add_u32_e32 v5, 1, v7
	s_nop 0
	v_cndmask_b32_e32 v3, v3, v6, vcc
	v_mul_lo_u32 v6, v4, v3
	v_add_u32_e32 v4, v6, v4
	v_cmp_ne_u32_e32 vcc, v5, v4
	s_and_saveexec_b64 s[6:7], vcc
	v_readlane_b32 s46, v255, 5
	s_xor_b64 s[6:7], exec, s[6:7]
	v_readlane_b32 s47, v255, 6
	s_cbranch_execz .LBB0_332
	s_waitcnt lgkmcnt(0)
	v_add_u32_e32 v3, 1, v3
	v_mul_lo_u32 v3, v3, v2
	v_mov_b32_e32 v2, 0x2000
	global_load_dword v2, v2, s[4:5] offset:1024 sc1
	s_add_u32 s12, s4, 0x2400
	s_addc_u32 s13, s5, 0
	s_waitcnt vmcnt(0)
	v_cmp_lt_u32_e32 vcc, v2, v3
	s_and_saveexec_b64 s[8:9], vcc
	s_cbranch_execz .LBB0_331
	s_add_u32 s10, s2, 0x1200
	s_addc_u32 s11, s3, 0
	s_mov_b32 s24, 1
	s_mov_b64 s[14:15], 0
	s_branch .LBB0_322

; __device__ __forceinline__ unsigned xb_ld(unsigned* p)              { return __hip_atomic_load(p, __ATOMIC_RELAXED, __HIP_MEMORY_SCOPE_AGENT); }
; #define XB_SPIN(cond, bar) do { unsigned _sp = 0; while (cond) { __builtin_amdgcn_s_sleep(1); \
;     if ((++_sp & 255u) == 0u) { if (xb_ld(&(bar)[XB_TMO])) break; if (_sp > XB_SPIN_CAP) { atomicAdd(&(bar)[XB_TMO], 1u); break; } } } } while (0)
; __device__ __forceinline__ void xcd_barrier(const XcdBarrier& b) {
;     ...
;             XB_SPIN(xb_ld(&bar[XB_XGEN(b.x)]) == gen, bar);
.LBB0_324:
	global_load_dword v2, v35, s[12:13] sc1
	s_add_i32 s24, s24, 1
	s_mov_b64 s[20:21], -1
	s_waitcnt vmcnt(0)
	v_cmp_ge_u32_e32 vcc, v2, v3
	s_orn2_b64 s[18:19], vcc, exec
	s_branch .LBB0_321

; __device__ __forceinline__ unsigned xb_ld(unsigned* p)              { return __hip_atomic_load(p, __ATOMIC_RELAXED, __HIP_MEMORY_SCOPE_AGENT); }
; __device__ __forceinline__ unsigned xb_add(unsigned* p, unsigned v) { return __hip_atomic_fetch_add(p, v, __ATOMIC_RELAXED, __HIP_MEMORY_SCOPE_AGENT); }
; #define XB_SPIN(cond, bar) do { unsigned _sp = 0; while (cond) { __builtin_amdgcn_s_sleep(1); \
;     if ((++_sp & 255u) == 0u) { if (xb_ld(&(bar)[XB_TMO])) break; if (_sp > XB_SPIN_CAP) { atomicAdd(&(bar)[XB_TMO], 1u); break; } } } } while (0)
; __device__ __forceinline__ void xcd_barrier(const XcdBarrier& b) {
;     ...
;         if (old + 1u == (gen + 1u) * nloc) {
;             __builtin_amdgcn_fence(__ATOMIC_RELEASE, "agent");
;             asm volatile("s_waitcnt vmcnt(0)" ::: "memory");
;             const unsigned og = xb_add(&bar[XB_TOP], 1u);
;             const unsigned tg = og / nx;
;             if (og + 1u == (tg + 1u) * nx) xb_add(&bar[XB_TOPGEN], 1u);
;             else XB_SPIN(xb_ld(&bar[XB_TOPGEN]) == tg, bar);
;             __builtin_amdgcn_fence(__ATOMIC_ACQUIRE, "agent");
;             xb_add(&bar[XB_XGEN(b.x)], 1u);
;             asm volatile("s_waitcnt vmcnt(0)" ::: "memory");
;         } else {
;             XB_SPIN(xb_ld(&bar[XB_XGEN(b.x)]) == gen, bar);
;             __builtin_amdgcn_fence(__ATOMIC_ACQUIRE, "agent");
;             asm volatile("s_waitcnt vmcnt(0)" ::: "memory");
.LBB0_332:
	s_andn2_saveexec_b64 s[6:7], s[6:7]
	s_cbranch_execz .LBB0_352
	s_mov_b64 s[6:7], exec
	buffer_wbl2 sc1
	s_waitcnt lgkmcnt(0)
	s_waitcnt vmcnt(0)
	v_add_u32_e32 v3, 1, v3
	v_mul_lo_u32 v3, v3, v2
	v_mov_b32_e32 v5, 0x3400
	v_mov_b32_e32 v6, 1
	global_atomic_add v5, v6, s[2:3]
	global_atomic_add v5, v6, s[2:3] offset:256
	global_atomic_add v5, v6, s[2:3] offset:512
	global_atomic_add v5, v6, s[2:3] offset:768
	global_atomic_add v5, v6, s[2:3] offset:1024
	global_atomic_add v5, v6, s[2:3] offset:1280
	global_atomic_add v5, v6, s[2:3] offset:1536
	global_atomic_add v5, v6, s[2:3] offset:1792
	global_atomic_add v5, v6, s[2:3] offset:2048
	global_atomic_add v5, v6, s[2:3] offset:2304
	global_atomic_add v5, v6, s[2:3] offset:2560
	global_atomic_add v5, v6, s[2:3] offset:2816
	global_atomic_add v5, v6, s[2:3] offset:3072
	global_atomic_add v5, v6, s[2:3] offset:3328
	global_atomic_add v5, v6, s[2:3] offset:3584
	global_atomic_add v5, v6, s[2:3] offset:3840
	s_add_u32 s8, s4, 0x2400
	s_addc_u32 s9, s5, 0
	v_mov_b32_e32 v4, 0
	s_mov_b32 s10, 0

; __device__ __forceinline__ unsigned xb_ld(unsigned* p)              { return __hip_atomic_load(p, __ATOMIC_RELAXED, __HIP_MEMORY_SCOPE_AGENT); }
; __device__ __forceinline__ unsigned xb_add(unsigned* p, unsigned v) { return __hip_atomic_fetch_add(p, v, __ATOMIC_RELAXED, __HIP_MEMORY_SCOPE_AGENT); }
; #define XB_SPIN(cond, bar) do { unsigned _sp = 0; while (cond) { __builtin_amdgcn_s_sleep(1); \
;     if ((++_sp & 255u) == 0u) { if (xb_ld(&(bar)[XB_TMO])) break; if (_sp > XB_SPIN_CAP) { atomicAdd(&(bar)[XB_TMO], 1u); break; } } } } while (0)
; __device__ __forceinline__ void xcd_barrier(const XcdBarrier& b) {
;     ...
;         const unsigned old = xb_add(&bar[XB_XSUB(b.x)], 1u);
;         const unsigned gen = old / nloc;
;         if (old + 1u == (gen + 1u) * nloc) {
;     ...
;             XB_SPIN(xb_ld(&bar[XB_XGEN(b.x)]) == gen, bar);
.LBB0_938:
	s_or_b64 exec, exec, s[8:9]
	v_cvt_f32_u32_e32 v6, v4
	s_waitcnt vmcnt(0)
	v_readfirstlane_b32 s6, v5
	v_sub_u32_e32 v5, 0, v4
	v_rcp_iflag_f32_e32 v6, v6
	v_add_u32_e32 v7, s6, v3
	v_mul_f32_e32 v6, 0x4f7ffffe, v6
	v_cvt_u32_f32_e32 v6, v6
	v_mul_lo_u32 v3, v5, v6
	v_mul_hi_u32 v3, v6, v3
	v_add_u32_e32 v3, v6, v3
	v_mul_hi_u32 v3, v7, v3
	v_mul_lo_u32 v5, v3, v4
	v_sub_u32_e32 v5, v7, v5
	v_add_u32_e32 v6, 1, v3
	v_cmp_ge_u32_e32 vcc, v5, v4
	s_nop 1
	v_cndmask_b32_e32 v3, v3, v6, vcc
	v_sub_u32_e32 v6, v5, v4
	v_cndmask_b32_e32 v5, v5, v6, vcc
	v_add_u32_e32 v6, 1, v3
	v_cmp_ge_u32_e32 vcc, v5, v4
	v_add_u32_e32 v5, 1, v7
	s_nop 0
	v_cndmask_b32_e32 v3, v3, v6, vcc
	v_mul_lo_u32 v6, v4, v3
	v_add_u32_e32 v4, v6, v4
	v_cmp_ne_u32_e32 vcc, v5, v4
	s_and_saveexec_b64 s[6:7], vcc
	s_xor_b64 s[6:7], exec, s[6:7]
	s_cbranch_execz .LBB0_952
	s_waitcnt lgkmcnt(0)
	v_add_u32_e32 v3, 1, v3
	v_mul_lo_u32 v3, v3, v2
	v_mov_b32_e32 v2, 0x2000
	global_load_dword v2, v2, s[4:5] offset:1024 sc1
	s_add_u32 s12, s4, 0x2400
	s_addc_u32 s13, s5, 0
	s_waitcnt vmcnt(0)
	v_cmp_lt_u32_e32 vcc, v2, v3
	s_and_saveexec_b64 s[8:9], vcc
	s_cbranch_execz .LBB0_951
	s_add_u32 s10, s2, 0x1200
	s_addc_u32 s11, s3, 0
	s_mov_b32 s24, 1
	s_mov_b64 s[14:15], 0
	s_branch .LBB0_942

; __device__ __forceinline__ unsigned xb_ld(unsigned* p)              { return __hip_atomic_load(p, __ATOMIC_RELAXED, __HIP_MEMORY_SCOPE_AGENT); }
; __device__ __forceinline__ unsigned xb_add(unsigned* p, unsigned v) { return __hip_atomic_fetch_add(p, v, __ATOMIC_RELAXED, __HIP_MEMORY_SCOPE_AGENT); }
; #define XB_SPIN(cond, bar) do { unsigned _sp = 0; while (cond) { __builtin_amdgcn_s_sleep(1); \
;     if ((++_sp & 255u) == 0u) { if (xb_ld(&(bar)[XB_TMO])) break; if (_sp > XB_SPIN_CAP) { atomicAdd(&(bar)[XB_TMO], 1u); break; } } } } while (0)
; __device__ __forceinline__ void xcd_barrier(const XcdBarrier& b) {
;     ...
;         if (old + 1u == (gen + 1u) * nloc) {
;             __builtin_amdgcn_fence(__ATOMIC_RELEASE, "agent");
;             asm volatile("s_waitcnt vmcnt(0)" ::: "memory");
;             const unsigned og = xb_add(&bar[XB_TOP], 1u);
;             const unsigned tg = og / nx;
;             if (og + 1u == (tg + 1u) * nx) xb_add(&bar[XB_TOPGEN], 1u);
;             else XB_SPIN(xb_ld(&bar[XB_TOPGEN]) == tg, bar);
;             __builtin_amdgcn_fence(__ATOMIC_ACQUIRE, "agent");
;             xb_add(&bar[XB_XGEN(b.x)], 1u);
;             asm volatile("s_waitcnt vmcnt(0)" ::: "memory");
;         } else {
;             XB_SPIN(xb_ld(&bar[XB_XGEN(b.x)]) == gen, bar);
;             __builtin_amdgcn_fence(__ATOMIC_ACQUIRE, "agent");
;             asm volatile("s_waitcnt vmcnt(0)" ::: "memory");
.LBB0_1047:
	s_mov_b64 s[6:7], exec
	buffer_wbl2 sc1
	s_waitcnt lgkmcnt(0)
	s_waitcnt vmcnt(0)
	v_add_u32_e32 v3, 1, v3
	v_mul_lo_u32 v3, v3, v2
	v_mov_b32_e32 v5, 0x3400
	v_mov_b32_e32 v6, 1
	global_atomic_add v5, v6, s[2:3]
	global_atomic_add v5, v6, s[2:3] offset:256
	global_atomic_add v5, v6, s[2:3] offset:512
	global_atomic_add v5, v6, s[2:3] offset:768
	global_atomic_add v5, v6, s[2:3] offset:1024
	global_atomic_add v5, v6, s[2:3] offset:1280
	global_atomic_add v5, v6, s[2:3] offset:1536
	global_atomic_add v5, v6, s[2:3] offset:1792
	global_atomic_add v5, v6, s[2:3] offset:2048
	global_atomic_add v5, v6, s[2:3] offset:2304
	global_atomic_add v5, v6, s[2:3] offset:2560
	global_atomic_add v5, v6, s[2:3] offset:2816
	global_atomic_add v5, v6, s[2:3] offset:3072
	global_atomic_add v5, v6, s[2:3] offset:3328
	global_atomic_add v5, v6, s[2:3] offset:3584
	global_atomic_add v5, v6, s[2:3] offset:3840
	s_add_u32 s8, s4, 0x2400
	s_addc_u32 s9, s5, 0
	v_mov_b32_e32 v4, 0
	s_mov_b32 s10, 0

; __device__ __forceinline__ void xcd_barrier(const XcdBarrier& b) {
;     ...
;             __builtin_amdgcn_fence(__ATOMIC_ACQUIRE, "agent");
;             asm volatile("s_waitcnt vmcnt(0)" ::: "memory");
.Lxb_done_0:
	s_waitcnt vmcnt(0)
	buffer_inv sc1
	s_waitcnt vmcnt(0)
	s_getpc_b64 s[98:99]
